# GLA scan: staging-write vmcnt waits use the steady-state count (22) when the five intervening load blocks were issued in-loop, conservative 10 on first iteration and tail
# baseline (speedup 1.0000x reference)
; DI void gla_scan_item(const P& p, int seq, unsigned char* smem) {
;     ...
;     auto loadr = [&](GlaRegs& R, int c) {
;         if (c >= 72) return;
;         { const int pos = tid >> 4, ch = tid & 15; R.rv = *(const u32x4*)(S + (size_t)prow(b, dir, 32 * c + pos) * NP + C_GLA_V + 128 * h + 8 * ch); }
;         { const int t2 = tid & 255, pos = t2 >> 3, ch = t2 & 7; const bf16_t* src = (tid < 256 ? QT : KO) + ((size_t)seq * PT + 32 * c + pos) * 64 + 8 * ch; R.rq = __builtin_nontemporal_load((const u32x4*)src); }
;         if (tid < 128) { const int i = tid >> 2, ch = tid & 3; R.ra = __builtin_nontemporal_load((const u32x4*)(AT + (((size_t)seq * 72 + c) * 32 + i) * 32 + 8 * ch)); }
;         if (tid >= 128 && tid < 192) R.rd = DC[((size_t)seq * 72 + c) * 64 + (tid - 128)];
;     };
;     auto storel = [&](const GlaRegs& R, int buf) {
;         unsigned char* base = smem + buf * BUFB;
;         bf16_t* sat = (bf16_t*)base; bf16_t* sqt = (bf16_t*)(base + 2560); bf16_t* sko = (bf16_t*)(base + 2560 + 4608); bf16_t* sv = (bf16_t*)(base + 2560 + 9216); float* sdc = (float*)(base + 2560 + 9216 + 8704);
;         { const int pos = tid >> 4, ch = tid & 15; *(u32x4*)(sv + pos * 136 + 8 * ch) = R.rv; }
;         { const int t2 = tid & 255, pos = t2 >> 3, ch = t2 & 7; *(u32x4*)((tid < 256 ? sqt : sko) + pos * 72 + 8 * ch) = R.rq; }
;         if (tid < 128) { const int i = tid >> 2, ch = tid & 3; *(u32x4*)(sat + i * 40 + 8 * ch) = R.ra; }
;         if (tid >= 128 && tid < 192) sdc[tid - 128] = R.rd;
;     };
;     ...
; #pragma unroll 1
;     for (int c = 0; c < 72; c += 6) {
;         storel(R0, 0); __syncthreads(); loadr(R0, c + 6); compute(c);
.LBB0_580:
	s_cmp_le_u32 s24, 60
	s_cbranch_scc0 .Lgla_wcons_1
	s_waitcnt vmcnt(22)
	s_branch .Lgla_wdone_1
.Lgla_wcons_1:
	s_waitcnt vmcnt(10)
.Lgla_wdone_1:
	ds_write_b128 v121, v[0:3] offset:11776
	ds_write_b128 v122, v[8:11]
	s_and_saveexec_b64 s[36:37], s[38:39]
	ds_write_b128 v148, v[4:7]
	s_or_b64 exec, exec, s[36:37]
	s_and_saveexec_b64 s[36:37], s[40:41]
	ds_write_b32 v149, v115 offset:19968
	s_or_b64 exec, exec, s[36:37]
	s_add_i32 s24, s24, 6
	s_cmpk_gt_u32 s24, 0x41
	v_add_u32_e32 v150, s26, v114
	v_lshl_add_u64 v[112:113], v[108:109], 0, s[44:45]
	s_waitcnt lgkmcnt(0)
	s_barrier
	ds_read_b64_tr_b16 v[200:201], v123 offset:11776
	ds_read_b64_tr_b16 v[202:203], v124 offset:11776
	ds_read_b128 v[204:207], v125
	ds_read_b128 v[216:219], v127
	ds_read_b64_tr_b16 v[238:239], v144 offset:7168
	ds_read_b64_tr_b16 v[242:243], v144 offset:7200
	ds_read_b64_tr_b16 v[236:237], v143 offset:7168
	ds_read_b64_tr_b16 v[240:241], v143 offset:7200
	ds_read_b64_tr_b16 v[248:249], v143 offset:7232
	ds_read_b64_tr_b16 v[250:251], v144 offset:7232
	s_cbranch_scc1 .LBB0_590
	v_add_u32_e32 v0, 0x80, v150
	s_movk_i32 s2, 0x100
	v_cmp_gt_i32_e32 vcc, s2, v0
	v_add_u32_e32 v1, 0xffffff80, v150
	v_mov_b32_e32 v3, s22
	v_cndmask_b32_e32 v2, v174, v175, vcc
	v_add3_u32 v2, v132, v2, s27
	v_cndmask_b32_e32 v0, v1, v0, vcc
	v_mov_b32_e32 v1, s21
	v_add_u32_e32 v2, 0xfffff6e1, v2
	v_cndmask_b32_e32 v1, v1, v3, vcc
	v_cndmask_b32_e64 v0, v2, v0, s[0:1]
	v_add_u32_e32 v0, v0, v1
	s_movk_i32 s2, 0x3800
	v_add_co_u32_e32 v8, vcc, 0x6000, v112
	v_mad_i64_i32 v[0:1], s[2:3], v0, s2, v[104:105]
	s_nop 0
	v_addc_co_u32_e32 v9, vcc, 0, v113, vcc
	global_load_dwordx4 v[0:3], v[0:1], off offset:1024
	s_nop 0
	global_load_dwordx4 v[8:11], v[8:9], off nt
	s_and_saveexec_b64 s[36:37], s[38:39]
	s_cbranch_execz .LBB0_587
	v_lshl_add_u64 v[4:5], v[106:107], 0, s[44:45]
	v_add_co_u32_e32 v4, vcc, 0x1283f000, v4
	s_nop 1
	v_addc_co_u32_e32 v5, vcc, 0, v5, vcc
	global_load_dwordx4 v[4:7], v[4:5], off nt

; DI bf16x8 tr2(const bf16_t* p0, const bf16_t* p1) { s16x4 a = trread(p0), b = trread(p1); return __builtin_shufflevector(a, b, 0, 1, 2, 3, 4, 5, 6, 7); }
; DI f32x4 mfma16(bf16x8 a, bf16x8 b, f32x4 c) { return __builtin_amdgcn_mfma_f32_16x16x32_bf16(a, b, c, 0, 0, 0); }
; DI void gla_scan_item(const P& p, int seq, unsigned char* smem) {
;     ...
;     auto compute = [&](int c) {
;         const unsigned char* base = smem + (c & 1) * BUFB;
;         const bf16_t* sat = (const bf16_t*)base; const bf16_t* sqt = (const bf16_t*)(base + 2560); const bf16_t* sko = (const bf16_t*)(base + 2560 + 4608); const bf16_t* sv = (const bf16_t*)(base + 2560 + 9216); const float* sdc = (const float*)(base + 2560 + 9216 + 8704);
;         const int dv0 = 16 * w;
;         const bf16x8 vb = tr2(sv + (8 * g + q4) * 136 + dv0 + 4 * p4, sv + (8 * g + 4 + q4) * 136 + dv0 + 4 * p4);
;         bf16x8 bs[2];
;         bs[0] = packacc(st[0], st[1]); bs[1] = packacc(st[2], st[3]);
; #pragma unroll
;         for (int mt = 0; mt < 2; ++mt) {
;             f32x4 acc = (f32x4){0.f, 0.f, 0.f, 0.f};
;             acc = mfma16(vb, ld8(sat + (16 * mt + l15) * 40 + 8 * g), acc);
; #pragma unroll
;             for (int ks = 0; ks < 2; ++ks) {
;                 const bf16_t* r0 = sqt + (16 * mt + l15) * 72 + 32 * ks + 4 * g;
;                 acc = mfma16(bs[ks], ld4x2(r0, r0 + 16), acc);
;             }
;             bf16_t* ob = OG + (size_t)prow(b, dir, 32 * c) * 512 + 128 * h;
;             u32x2 ov; ov.x = pk2(acc[0], acc[1]); ov.y = pk2(acc[2], acc[3]);
;             *(u32x2*)(ob + sgn * ((16 * mt + l15) * 512) + dv0 + 4 * g) = ov;
;         }
; #pragma unroll
;         for (int dt = 0; dt < 4; ++dt) {
;             const bf16x8 ak = tr2(sko + (8 * g + q4) * 72 + 16 * dt + 4 * p4, sko + (8 * g + 4 + q4) * 72 + 16 * dt + 4 * p4);
; #pragma unroll
;             for (int r = 0; r < 4; ++r) st[dt][r] *= sdc[16 * dt + 4 * g + r];
;             st[dt] = mfma16(ak, vb, st[dt]);
;         }
;     };
.LBB0_590:
	v_cvt_pk_bf16_f32 v96, v84, v85
	v_cvt_pk_bf16_f32 v99, v78, v79
	v_add_u32_e32 v152, 0x800, v126
	ds_read2_b64 v[208:211], v152 offset0:64 offset1:68
	ds_read2_b64 v[212:215], v152 offset0:72 offset1:76
	v_cvt_pk_bf16_f32 v98, v76, v77
	v_cvt_pk_bf16_f32 v97, v86, v87
	s_sub_i32 s4, s26, 64
	s_add_i32 s5, s26, 0xfffffec0
	s_add_i32 s6, s27, 0xa0
	s_add_i32 s7, s27, 0xfffff8a0
	s_waitcnt lgkmcnt(9)
	v_mfma_f32_16x16x32_bf16 v[92:95], v[200:203], v[204:207], 0
	s_and_b64 s[2:3], s[0:1], exec
	s_cselect_b32 s2, s4, s7
	s_add_i32 s4, s2, s22
	s_and_b64 s[2:3], s[0:1], exec
	s_waitcnt lgkmcnt(1)
	v_mfma_f32_16x16x32_bf16 v[92:95], v[96:99], v[208:211], v[92:95]
	ds_read_b64_tr_b16 v[208:209], v143 offset:7264
	ds_read_b64_tr_b16 v[210:211], v144 offset:7264
	v_cvt_pk_bf16_f32 v156, v72, v73
	v_cvt_pk_bf16_f32 v155, v82, v83
	v_cvt_pk_bf16_f32 v154, v80, v81
	v_cvt_pk_bf16_f32 v157, v74, v75
	s_cselect_b32 s2, s5, s6
	s_add_i32 s5, s2, s21
	s_cmp_lt_u32 s24, 8
	s_cselect_b64 s[36:37], -1, 0
	s_waitcnt lgkmcnt(2)
	v_mfma_f32_16x16x32_bf16 v[92:95], v[154:157], v[212:215], v[92:95]
	s_and_b64 s[2:3], s[36:37], exec
	s_cselect_b32 s2, s4, s5
	s_ashr_i32 s3, s2, 31
	s_lshl_b64 s[42:43], s[2:3], 10
	v_add_u32_e32 v151, 0x800, v142
	ds_read2_b64 v[224:227], v151 offset0:64 offset1:68
	ds_read2_b64 v[228:231], v151 offset0:72 offset1:76
	s_nop 2
	v_cvt_pk_bf16_f32 v92, v92, v93
	v_cvt_pk_bf16_f32 v93, v94, v95
	v_lshl_add_u64 v[94:95], v[100:101], 0, s[42:43]
	global_store_dwordx2 v[94:95], v[92:93], off
	v_mfma_f32_16x16x32_bf16 v[92:95], v[200:203], v[216:219], 0
	v_add_u32_e32 v153, 0x5000, v145
	ds_read2_b32 v[232:233], v153 offset1:1
	s_waitcnt lgkmcnt(2)
	v_mfma_f32_16x16x32_bf16 v[92:95], v[96:99], v[224:227], v[92:95]
	v_add_u32_e32 v158, 0x5040, v145
	ds_read2_b32 v[244:245], v158 offset1:1
	v_add_u32_e32 v161, 0x50c0, v145
	ds_read2_b32 v[212:213], v161 offset1:1
	s_waitcnt lgkmcnt(3)
	v_mfma_f32_16x16x32_bf16 v[92:95], v[154:157], v[228:231], v[92:95]
	v_add_u32_e32 v156, 0x5008, v145
	ds_read2_b32 v[234:235], v156 offset1:1
	v_add_u32_e32 v157, 0x5048, v145
	ds_read2_b32 v[246:247], v157 offset1:1
	v_add_u32_e32 v154, 0x5080, v145
	ds_read2_b32 v[204:205], v154 offset1:1
	s_nop 4
	v_cvt_pk_bf16_f32 v92, v92, v93
	v_cvt_pk_bf16_f32 v93, v94, v95
	v_lshl_add_u64 v[94:95], v[102:103], 0, s[42:43]
	global_store_dwordx2 v[94:95], v[92:93], off
	v_add_u32_e32 v155, 0x5088, v145
	ds_read2_b32 v[206:207], v155 offset1:1
	v_add_u32_e32 v160, 0x50c8, v145
	ds_read2_b32 v[214:215], v160 offset1:1
	s_waitcnt lgkmcnt(7)
	v_pk_mul_f32 v[84:85], v[84:85], v[232:233]
	s_waitcnt lgkmcnt(4)
	v_pk_mul_f32 v[86:87], v[86:87], v[234:235]
	s_nop 1
	v_mfma_f32_16x16x32_bf16 v[84:87], v[236:239], v[200:203], v[84:87]
	v_pk_mul_f32 v[76:77], v[76:77], v[244:245]
	s_waitcnt lgkmcnt(3)
	v_pk_mul_f32 v[78:79], v[78:79], v[246:247]
	s_nop 1
	v_mfma_f32_16x16x32_bf16 v[76:79], v[240:243], v[200:203], v[76:79]
	s_waitcnt lgkmcnt(2)
	v_pk_mul_f32 v[80:81], v[80:81], v[204:205]
	s_waitcnt lgkmcnt(1)
	v_pk_mul_f32 v[82:83], v[82:83], v[206:207]
	s_nop 1
	v_mfma_f32_16x16x32_bf16 v[80:83], v[248:251], v[200:203], v[80:83]
	s_sub_u32 s98, s24, 6
	s_cmp_le_u32 s98, 59
	s_cbranch_scc0 .Lgla_wcons_2
	s_waitcnt vmcnt(22)
	s_branch .Lgla_wdone_2

; DI bf16x8 tr2(const bf16_t* p0, const bf16_t* p1) { s16x4 a = trread(p0), b = trread(p1); return __builtin_shufflevector(a, b, 0, 1, 2, 3, 4, 5, 6, 7); }
; DI f32x4 mfma16(bf16x8 a, bf16x8 b, f32x4 c) { return __builtin_amdgcn_mfma_f32_16x16x32_bf16(a, b, c, 0, 0, 0); }
; DI void gla_scan_item(const P& p, int seq, unsigned char* smem) {
;     ...
;     auto loadr = [&](GlaRegs& R, int c) {
;         if (c >= 72) return;
;         { const int pos = tid >> 4, ch = tid & 15; R.rv = *(const u32x4*)(S + (size_t)prow(b, dir, 32 * c + pos) * NP + C_GLA_V + 128 * h + 8 * ch); }
;         { const int t2 = tid & 255, pos = t2 >> 3, ch = t2 & 7; const bf16_t* src = (tid < 256 ? QT : KO) + ((size_t)seq * PT + 32 * c + pos) * 64 + 8 * ch; R.rq = __builtin_nontemporal_load((const u32x4*)src); }
;         if (tid < 128) { const int i = tid >> 2, ch = tid & 3; R.ra = __builtin_nontemporal_load((const u32x4*)(AT + (((size_t)seq * 72 + c) * 32 + i) * 32 + 8 * ch)); }
;         if (tid >= 128 && tid < 192) R.rd = DC[((size_t)seq * 72 + c) * 64 + (tid - 128)];
;     };
;     auto storel = [&](const GlaRegs& R, int buf) {
;         unsigned char* base = smem + buf * BUFB;
;         bf16_t* sat = (bf16_t*)base; bf16_t* sqt = (bf16_t*)(base + 2560); bf16_t* sko = (bf16_t*)(base + 2560 + 4608); bf16_t* sv = (bf16_t*)(base + 2560 + 9216); float* sdc = (float*)(base + 2560 + 9216 + 8704);
;         { const int pos = tid >> 4, ch = tid & 15; *(u32x4*)(sv + pos * 136 + 8 * ch) = R.rv; }
;         { const int t2 = tid & 255, pos = t2 >> 3, ch = t2 & 7; *(u32x4*)((tid < 256 ? sqt : sko) + pos * 72 + 8 * ch) = R.rq; }
;         if (tid < 128) { const int i = tid >> 2, ch = tid & 3; *(u32x4*)(sat + i * 40 + 8 * ch) = R.ra; }
;         if (tid >= 128 && tid < 192) sdc[tid - 128] = R.rd;
;     };
;     ...
;         for (int dt = 0; dt < 4; ++dt) {
;             const bf16x8 ak = tr2(sko + (8 * g + q4) * 72 + 16 * dt + 4 * p4, sko + (8 * g + 4 + q4) * 72 + 16 * dt + 4 * p4);
; #pragma unroll
;             for (int r = 0; r < 4; ++r) st[dt][r] *= sdc[16 * dt + 4 * g + r];
;             st[dt] = mfma16(ak, vb, st[dt]);
;         }
;     };
.Lgla_wdone_2:
	ds_write_b128 v121, v[12:15] offset:32512
	ds_write_b128 v122, v[20:23] offset:20736
	v_pk_mul_f32 v[72:73], v[72:73], v[212:213]
	s_waitcnt lgkmcnt(2)
	v_pk_mul_f32 v[74:75], v[74:75], v[214:215]
	s_nop 1
	v_mfma_f32_16x16x32_bf16 v[72:75], v[208:211], v[200:203], v[72:75]
	s_and_saveexec_b64 s[42:43], s[38:39]
	ds_write_b128 v148, v[16:19] offset:20736
	s_or_b64 exec, exec, s[42:43]
	s_and_saveexec_b64 s[42:43], s[40:41]
	ds_write_b32 v149, v116 offset:40704
	s_or_b64 exec, exec, s[42:43]
	s_cmp_gt_u32 s24, 64
	s_waitcnt lgkmcnt(0)
	s_barrier
	ds_read_b64_tr_b16 v[200:201], v123 offset:32512
	ds_read_b64_tr_b16 v[202:203], v124 offset:32512
	ds_read_b128 v[204:207], v125 offset:20736
	ds_read_b128 v[216:219], v127 offset:20736
	ds_read_b64_tr_b16 v[238:239], v147 offset:27904
	ds_read_b64_tr_b16 v[242:243], v147 offset:27936
	ds_read_b64_tr_b16 v[236:237], v146 offset:27904
	ds_read_b64_tr_b16 v[240:241], v146 offset:27936
	ds_read_b64_tr_b16 v[248:249], v146 offset:27968
	ds_read_b64_tr_b16 v[250:251], v147 offset:27968
	s_cbranch_scc1 .LBB0_600
	v_add_u32_e32 v12, 0xa0, v150
	s_movk_i32 s2, 0x100
	v_cmp_gt_i32_e32 vcc, s2, v12
	v_add_u32_e32 v13, 0xffffffa0, v150
	v_mov_b32_e32 v15, s22
	v_cndmask_b32_e32 v14, v174, v175, vcc
	v_add3_u32 v14, v132, v14, s27
	v_cndmask_b32_e32 v12, v13, v12, vcc
	v_mov_b32_e32 v13, s21
	v_add_u32_e32 v14, 0xfffff6c1, v14
	v_cndmask_b32_e32 v13, v13, v15, vcc
	v_cndmask_b32_e64 v12, v14, v12, s[0:1]
	v_add_u32_e32 v12, v12, v13
	s_movk_i32 s2, 0x3800
	v_add_co_u32_e32 v20, vcc, 0x7000, v112
	v_mad_i64_i32 v[12:13], s[2:3], v12, s2, v[104:105]
	s_nop 0
	v_addc_co_u32_e32 v21, vcc, 0, v113, vcc
	global_load_dwordx4 v[12:15], v[12:13], off offset:1024
	s_nop 0
	global_load_dwordx4 v[20:23], v[20:21], off nt
	s_and_saveexec_b64 s[42:43], s[38:39]
	s_cbranch_execz .LBB0_597
	v_lshl_add_u64 v[16:17], v[106:107], 0, s[44:45]
	v_add_co_u32_e32 v16, vcc, 0x1283f000, v16
	s_nop 1
	v_addc_co_u32_e32 v17, vcc, 0, v17, vcc
	global_load_dwordx4 v[16:19], v[16:17], off offset:2048 nt

; DI bf16x8 tr2(const bf16_t* p0, const bf16_t* p1) { s16x4 a = trread(p0), b = trread(p1); return __builtin_shufflevector(a, b, 0, 1, 2, 3, 4, 5, 6, 7); }
; DI f32x4 mfma16(bf16x8 a, bf16x8 b, f32x4 c) { return __builtin_amdgcn_mfma_f32_16x16x32_bf16(a, b, c, 0, 0, 0); }
; DI void gla_scan_item(const P& p, int seq, unsigned char* smem) {
;     ...
;     auto compute = [&](int c) {
;         const unsigned char* base = smem + (c & 1) * BUFB;
;         const bf16_t* sat = (const bf16_t*)base; const bf16_t* sqt = (const bf16_t*)(base + 2560); const bf16_t* sko = (const bf16_t*)(base + 2560 + 4608); const bf16_t* sv = (const bf16_t*)(base + 2560 + 9216); const float* sdc = (const float*)(base + 2560 + 9216 + 8704);
;         const int dv0 = 16 * w;
;         const bf16x8 vb = tr2(sv + (8 * g + q4) * 136 + dv0 + 4 * p4, sv + (8 * g + 4 + q4) * 136 + dv0 + 4 * p4);
;         bf16x8 bs[2];
;         bs[0] = packacc(st[0], st[1]); bs[1] = packacc(st[2], st[3]);
; #pragma unroll
;         for (int mt = 0; mt < 2; ++mt) {
;             f32x4 acc = (f32x4){0.f, 0.f, 0.f, 0.f};
;             acc = mfma16(vb, ld8(sat + (16 * mt + l15) * 40 + 8 * g), acc);
; #pragma unroll
;             for (int ks = 0; ks < 2; ++ks) {
;                 const bf16_t* r0 = sqt + (16 * mt + l15) * 72 + 32 * ks + 4 * g;
;                 acc = mfma16(bs[ks], ld4x2(r0, r0 + 16), acc);
;             }
;             bf16_t* ob = OG + (size_t)prow(b, dir, 32 * c) * 512 + 128 * h;
;             u32x2 ov; ov.x = pk2(acc[0], acc[1]); ov.y = pk2(acc[2], acc[3]);
;             *(u32x2*)(ob + sgn * ((16 * mt + l15) * 512) + dv0 + 4 * g) = ov;
;         }
; #pragma unroll
;         for (int dt = 0; dt < 4; ++dt) {
;             const bf16x8 ak = tr2(sko + (8 * g + q4) * 72 + 16 * dt + 4 * p4, sko + (8 * g + 4 + q4) * 72 + 16 * dt + 4 * p4);
; #pragma unroll
;             for (int r = 0; r < 4; ++r) st[dt][r] *= sdc[16 * dt + 4 * g + r];
;             st[dt] = mfma16(ak, vb, st[dt]);
;         }
;     };
.LBB0_600:
	v_cvt_pk_bf16_f32 v96, v84, v85
	v_cvt_pk_bf16_f32 v99, v78, v79
	v_add_u32_e32 v159, 0x5800, v126
	ds_read2_b64 v[208:211], v159 offset0:96 offset1:100
	ds_read2_b64 v[212:215], v159 offset0:104 offset1:108
	v_cvt_pk_bf16_f32 v98, v76, v77
	v_cvt_pk_bf16_f32 v97, v86, v87
	s_waitcnt lgkmcnt(9)
	v_mfma_f32_16x16x32_bf16 v[88:91], v[200:203], v[204:207], 0
	s_sub_i32 s4, s26, 32
	s_add_i32 s5, s26, 0xfffffee0
	s_add_i32 s6, s27, 0x80
	s_add_i32 s7, s27, 0xfffff880
	s_and_b64 s[2:3], s[0:1], exec
	s_waitcnt lgkmcnt(1)
	v_mfma_f32_16x16x32_bf16 v[162:165], v[96:99], v[208:211], v[88:91]
	ds_read_b64_tr_b16 v[208:209], v146 offset:28000
	ds_read_b64_tr_b16 v[210:211], v147 offset:28000
	s_cselect_b32 s2, s4, s7
	s_add_i32 s4, s2, s22
	s_and_b64 s[2:3], s[0:1], exec
	v_cvt_pk_bf16_f32 v90, v72, v73
	v_cvt_pk_bf16_f32 v89, v82, v83
	v_cvt_pk_bf16_f32 v88, v80, v81
	v_cvt_pk_bf16_f32 v91, v74, v75
	s_cselect_b32 s2, s5, s6
	s_add_i32 s5, s2, s21
	s_waitcnt lgkmcnt(2)
	v_mfma_f32_16x16x32_bf16 v[162:165], v[88:91], v[212:215], v[162:165]
	s_and_b64 s[2:3], s[36:37], exec
	s_cselect_b32 s2, s4, s5
	s_ashr_i32 s3, s2, 31
	s_lshl_b64 s[36:37], s[2:3], 10
	s_nop 3
	v_cvt_pk_bf16_f32 v134, v162, v163
	v_cvt_pk_bf16_f32 v135, v164, v165
	v_lshl_add_u64 v[162:163], v[100:101], 0, s[36:37]
	global_store_dwordx2 v[162:163], v[134:135], off
	v_mfma_f32_16x16x32_bf16 v[184:187], v[200:203], v[216:219], 0
	v_add_u32_e32 v162, 0x5800, v142
	ds_read2_b64 v[224:227], v162 offset0:96 offset1:100
	ds_read2_b64 v[228:231], v162 offset0:104 offset1:108
	v_add_u32_e32 v163, 0xa100, v145
	ds_read2_b32 v[232:233], v163 offset1:1
	s_waitcnt lgkmcnt(2)
	v_mfma_f32_16x16x32_bf16 v[96:99], v[96:99], v[224:227], v[184:187]
	s_nop 2
	v_add_u32_e32 v183, 0xa108, v145
	ds_read2_b32 v[234:235], v183 offset1:1
	v_add_u32_e32 v164, 0xa180, v145
	ds_read2_b32 v[204:205], v164 offset1:1
	s_waitcnt lgkmcnt(3)
	v_mfma_f32_16x16x32_bf16 v[88:91], v[88:91], v[228:231], v[96:99]
	v_add_u32_e32 v185, 0xa140, v145
	ds_read2_b32 v[244:245], v185 offset1:1
	v_add_u32_e32 v184, 0xa148, v145
	ds_read2_b32 v[246:247], v184 offset1:1
	v_add_u32_e32 v165, 0xa188, v145
	ds_read2_b32 v[206:207], v165 offset1:1
	s_nop 4
	v_cvt_pk_bf16_f32 v88, v88, v89
	v_cvt_pk_bf16_f32 v89, v90, v91
	v_lshl_add_u64 v[90:91], v[102:103], 0, s[36:37]
	global_store_dwordx2 v[90:91], v[88:89], off
	v_add_u32_e32 v187, 0xa1c0, v145
	ds_read2_b32 v[212:213], v187 offset1:1
	v_add_u32_e32 v186, 0xa1c8, v145
	ds_read2_b32 v[214:215], v186 offset1:1
	s_waitcnt lgkmcnt(7)
	v_pk_mul_f32 v[84:85], v[84:85], v[232:233]
	s_waitcnt lgkmcnt(6)
	v_pk_mul_f32 v[86:87], v[86:87], v[234:235]
	s_nop 1
	v_mfma_f32_16x16x32_bf16 v[88:91], v[236:239], v[200:203], v[84:87]
	s_nop 2
	s_waitcnt lgkmcnt(4)
	v_pk_mul_f32 v[76:77], v[76:77], v[244:245]
	s_waitcnt lgkmcnt(3)
	v_pk_mul_f32 v[78:79], v[78:79], v[246:247]
	s_nop 1
	v_mfma_f32_16x16x32_bf16 v[84:87], v[240:243], v[200:203], v[76:79]
	s_nop 2
	v_pk_mul_f32 v[80:81], v[80:81], v[204:205]
	s_waitcnt lgkmcnt(2)
	v_pk_mul_f32 v[82:83], v[82:83], v[206:207]
	s_nop 1
	v_mfma_f32_16x16x32_bf16 v[76:79], v[248:251], v[200:203], v[80:83]
	s_nop 2
	s_sub_u32 s98, s24, 6
	s_cmp_le_u32 s98, 58
	s_cbranch_scc0 .Lgla_wcons_3
	s_waitcnt vmcnt(22)
	s_branch .Lgla_wdone_3

; DI bf16x8 tr2(const bf16_t* p0, const bf16_t* p1) { s16x4 a = trread(p0), b = trread(p1); return __builtin_shufflevector(a, b, 0, 1, 2, 3, 4, 5, 6, 7); }
; DI f32x4 mfma16(bf16x8 a, bf16x8 b, f32x4 c) { return __builtin_amdgcn_mfma_f32_16x16x32_bf16(a, b, c, 0, 0, 0); }
; DI void gla_scan_item(const P& p, int seq, unsigned char* smem) {
;     ...
;     auto loadr = [&](GlaRegs& R, int c) {
;         if (c >= 72) return;
;         { const int pos = tid >> 4, ch = tid & 15; R.rv = *(const u32x4*)(S + (size_t)prow(b, dir, 32 * c + pos) * NP + C_GLA_V + 128 * h + 8 * ch); }
;         { const int t2 = tid & 255, pos = t2 >> 3, ch = t2 & 7; const bf16_t* src = (tid < 256 ? QT : KO) + ((size_t)seq * PT + 32 * c + pos) * 64 + 8 * ch; R.rq = __builtin_nontemporal_load((const u32x4*)src); }
;         if (tid < 128) { const int i = tid >> 2, ch = tid & 3; R.ra = __builtin_nontemporal_load((const u32x4*)(AT + (((size_t)seq * 72 + c) * 32 + i) * 32 + 8 * ch)); }
;         if (tid >= 128 && tid < 192) R.rd = DC[((size_t)seq * 72 + c) * 64 + (tid - 128)];
;     };
;     auto storel = [&](const GlaRegs& R, int buf) {
;         unsigned char* base = smem + buf * BUFB;
;         bf16_t* sat = (bf16_t*)base; bf16_t* sqt = (bf16_t*)(base + 2560); bf16_t* sko = (bf16_t*)(base + 2560 + 4608); bf16_t* sv = (bf16_t*)(base + 2560 + 9216); float* sdc = (float*)(base + 2560 + 9216 + 8704);
;         { const int pos = tid >> 4, ch = tid & 15; *(u32x4*)(sv + pos * 136 + 8 * ch) = R.rv; }
;         { const int t2 = tid & 255, pos = t2 >> 3, ch = t2 & 7; *(u32x4*)((tid < 256 ? sqt : sko) + pos * 72 + 8 * ch) = R.rq; }
;         if (tid < 128) { const int i = tid >> 2, ch = tid & 3; *(u32x4*)(sat + i * 40 + 8 * ch) = R.ra; }
;         if (tid >= 128 && tid < 192) sdc[tid - 128] = R.rd;
;     };
;     ...
;         for (int dt = 0; dt < 4; ++dt) {
;             const bf16x8 ak = tr2(sko + (8 * g + q4) * 72 + 16 * dt + 4 * p4, sko + (8 * g + 4 + q4) * 72 + 16 * dt + 4 * p4);
; #pragma unroll
;             for (int r = 0; r < 4; ++r) st[dt][r] *= sdc[16 * dt + 4 * g + r];
;             st[dt] = mfma16(ak, vb, st[dt]);
;         }
;     };
.Lgla_wdone_3:
	ds_write_b128 v121, v[24:27] offset:11776
	ds_write_b128 v122, v[32:35]
	s_waitcnt lgkmcnt(3)
	v_pk_mul_f32 v[72:73], v[72:73], v[212:213]
	s_waitcnt lgkmcnt(2)
	v_pk_mul_f32 v[74:75], v[74:75], v[214:215]
	s_nop 1
	v_mfma_f32_16x16x32_bf16 v[80:83], v[208:211], v[200:203], v[72:75]
	s_and_saveexec_b64 s[36:37], s[38:39]
	ds_write_b128 v148, v[28:31]
	s_or_b64 exec, exec, s[36:37]
	s_and_saveexec_b64 s[36:37], s[40:41]
	ds_write_b32 v149, v117 offset:19968
	s_or_b64 exec, exec, s[36:37]
	s_cmp_gt_u32 s24, 63
	s_waitcnt lgkmcnt(0)
	s_barrier
	ds_read_b64_tr_b16 v[200:201], v123 offset:11776
	ds_read_b64_tr_b16 v[202:203], v124 offset:11776
	ds_read_b128 v[204:207], v125
	ds_read2_b64 v[208:211], v152 offset0:64 offset1:68
	ds_read2_b64 v[212:215], v152 offset0:72 offset1:76
	ds_read2_b64 v[216:219], v151 offset0:64 offset1:68
	ds_read_b128 v[224:227], v127
	ds_read2_b64 v[228:231], v151 offset0:72 offset1:76
	ds_read2_b32 v[232:233], v153 offset1:1
	ds_read2_b32 v[234:235], v156 offset1:1
	ds_read_b64_tr_b16 v[238:239], v144 offset:7168
	ds_read_b64_tr_b16 v[242:243], v144 offset:7200
	s_cbranch_scc1 .LBB0_610
	v_add_u32_e32 v24, 0xc0, v150
	s_movk_i32 s2, 0x100
	v_cmp_gt_i32_e32 vcc, s2, v24
	v_subrev_u32_e32 v25, 64, v150
	v_mov_b32_e32 v27, s22
	v_cndmask_b32_e32 v26, v174, v175, vcc
	v_add3_u32 v26, v132, v26, s27
	v_cndmask_b32_e32 v24, v25, v24, vcc
	v_mov_b32_e32 v25, s21
	v_add_u32_e32 v26, 0xfffff6a1, v26
	v_cndmask_b32_e32 v25, v25, v27, vcc
	v_cndmask_b32_e64 v24, v26, v24, s[0:1]
	v_add_u32_e32 v24, v24, v25
	s_movk_i32 s2, 0x3800
	v_add_co_u32_e32 v32, vcc, 0x8000, v112
	v_mad_i64_i32 v[24:25], s[2:3], v24, s2, v[104:105]
	s_nop 0
	v_addc_co_u32_e32 v33, vcc, 0, v113, vcc
	global_load_dwordx4 v[24:27], v[24:25], off offset:1024
	s_nop 0
	global_load_dwordx4 v[32:35], v[32:33], off nt
	s_and_saveexec_b64 s[36:37], s[38:39]
	s_cbranch_execz .LBB0_607
	v_lshl_add_u64 v[28:29], v[106:107], 0, s[44:45]
	v_add_co_u32_e32 v28, vcc, 0x12840000, v28
	s_nop 1
	v_addc_co_u32_e32 v29, vcc, 0, v29, vcc
	global_load_dwordx4 v[28:31], v[28:29], off nt

; DI bf16x8 tr2(const bf16_t* p0, const bf16_t* p1) { s16x4 a = trread(p0), b = trread(p1); return __builtin_shufflevector(a, b, 0, 1, 2, 3, 4, 5, 6, 7); }
; DI f32x4 mfma16(bf16x8 a, bf16x8 b, f32x4 c) { return __builtin_amdgcn_mfma_f32_16x16x32_bf16(a, b, c, 0, 0, 0); }
; DI void gla_scan_item(const P& p, int seq, unsigned char* smem) {
;     ...
;     auto compute = [&](int c) {
;         const unsigned char* base = smem + (c & 1) * BUFB;
;         const bf16_t* sat = (const bf16_t*)base; const bf16_t* sqt = (const bf16_t*)(base + 2560); const bf16_t* sko = (const bf16_t*)(base + 2560 + 4608); const bf16_t* sv = (const bf16_t*)(base + 2560 + 9216); const float* sdc = (const float*)(base + 2560 + 9216 + 8704);
;         const int dv0 = 16 * w;
;         const bf16x8 vb = tr2(sv + (8 * g + q4) * 136 + dv0 + 4 * p4, sv + (8 * g + 4 + q4) * 136 + dv0 + 4 * p4);
;         bf16x8 bs[2];
;         bs[0] = packacc(st[0], st[1]); bs[1] = packacc(st[2], st[3]);
; #pragma unroll
;         for (int mt = 0; mt < 2; ++mt) {
;             f32x4 acc = (f32x4){0.f, 0.f, 0.f, 0.f};
;             acc = mfma16(vb, ld8(sat + (16 * mt + l15) * 40 + 8 * g), acc);
; #pragma unroll
;             for (int ks = 0; ks < 2; ++ks) {
;                 const bf16_t* r0 = sqt + (16 * mt + l15) * 72 + 32 * ks + 4 * g;
;                 acc = mfma16(bs[ks], ld4x2(r0, r0 + 16), acc);
;             }
;             bf16_t* ob = OG + (size_t)prow(b, dir, 32 * c) * 512 + 128 * h;
;             u32x2 ov; ov.x = pk2(acc[0], acc[1]); ov.y = pk2(acc[2], acc[3]);
;             *(u32x2*)(ob + sgn * ((16 * mt + l15) * 512) + dv0 + 4 * g) = ov;
;         }
; #pragma unroll
;         for (int dt = 0; dt < 4; ++dt) {
;             const bf16x8 ak = tr2(sko + (8 * g + q4) * 72 + 16 * dt + 4 * p4, sko + (8 * g + 4 + q4) * 72 + 16 * dt + 4 * p4);
; #pragma unroll
;             for (int r = 0; r < 4; ++r) st[dt][r] *= sdc[16 * dt + 4 * g + r];
;             st[dt] = mfma16(ak, vb, st[dt]);
;         }
;     };
.LBB0_610:
	v_cvt_pk_bf16_f32 v98, v84, v85
	v_cvt_pk_bf16_f32 v97, v90, v91
	v_cvt_pk_bf16_f32 v96, v88, v89
	v_cvt_pk_bf16_f32 v99, v86, v87
	s_waitcnt lgkmcnt(9)
	v_mfma_f32_16x16x32_bf16 v[72:75], v[200:203], v[204:207], 0
	ds_read_b64_tr_b16 v[236:237], v143 offset:7168
	ds_read_b64_tr_b16 v[240:241], v143 offset:7200
	ds_read2_b32 v[244:245], v158 offset1:1
	s_add_i32 s4, s26, 0xffffff00
	s_add_i32 s5, s27, 0x60
	s_add_i32 s6, s27, 0xfffff860
	s_and_b64 s[2:3], s[0:1], exec
	s_cselect_b32 s2, s26, s6
	s_waitcnt lgkmcnt(11)
	v_mfma_f32_16x16x32_bf16 v[72:75], v[96:99], v[208:211], v[72:75]
	ds_read2_b32 v[246:247], v157 offset1:1
	v_cvt_pk_bf16_f32 v190, v80, v81
	v_cvt_pk_bf16_f32 v189, v78, v79
	v_cvt_pk_bf16_f32 v188, v76, v77
	v_cvt_pk_bf16_f32 v191, v82, v83
	s_add_i32 s6, s2, s22
	s_and_b64 s[2:3], s[0:1], exec
	s_cselect_b32 s2, s4, s5
	s_add_i32 s2, s2, s21
	s_cmp_lt_u32 s24, 6
	s_waitcnt lgkmcnt(11)
	v_mfma_f32_16x16x32_bf16 v[72:75], v[188:191], v[212:215], v[72:75]
	ds_read_b64_tr_b16 v[248:249], v143 offset:7232
	s_cselect_b32 s2, s6, s2
	s_ashr_i32 s3, s2, 31
	s_lshl_b64 s[36:37], s[2:3], 10
	s_nop 3
	v_cvt_pk_bf16_f32 v72, v72, v73
	v_cvt_pk_bf16_f32 v73, v74, v75
	v_lshl_add_u64 v[74:75], v[100:101], 0, s[36:37]
	global_store_dwordx2 v[74:75], v[72:73], off
	s_waitcnt lgkmcnt(10)
	v_mfma_f32_16x16x32_bf16 v[72:75], v[200:203], v[224:227], 0
	ds_read_b64_tr_b16 v[250:251], v144 offset:7232
	ds_read2_b32 v[204:205], v154 offset1:1
	v_mfma_f32_16x16x32_bf16 v[72:75], v[96:99], v[216:219], v[72:75]
	s_waitcnt lgkmcnt(11)
	v_mfma_f32_16x16x32_bf16 v[72:75], v[188:191], v[228:231], v[72:75]
	ds_read2_b32 v[206:207], v155 offset1:1
	s_nop 7
	v_cvt_pk_bf16_f32 v72, v72, v73
	v_cvt_pk_bf16_f32 v73, v74, v75
	v_lshl_add_u64 v[74:75], v[102:103], 0, s[36:37]
	global_store_dwordx2 v[74:75], v[72:73], off
	s_waitcnt lgkmcnt(11)
	v_pk_mul_f32 v[72:73], v[88:89], v[232:233]
	ds_read_b64_tr_b16 v[208:209], v143 offset:7264
	s_waitcnt lgkmcnt(11)
	v_pk_mul_f32 v[74:75], v[90:91], v[234:235]
	ds_read_b64_tr_b16 v[210:211], v144 offset:7264
	s_waitcnt lgkmcnt(9)
	v_mfma_f32_16x16x32_bf16 v[88:91], v[236:239], v[200:203], v[72:75]
	ds_read2_b32 v[212:213], v161 offset1:1
	ds_read2_b32 v[214:215], v160 offset1:1
	s_nop 2
	s_waitcnt lgkmcnt(9)
	v_pk_mul_f32 v[72:73], v[84:85], v[244:245]
	s_waitcnt lgkmcnt(8)
	v_pk_mul_f32 v[74:75], v[86:87], v[246:247]
	s_nop 1
	v_mfma_f32_16x16x32_bf16 v[72:75], v[240:243], v[200:203], v[72:75]
	s_waitcnt lgkmcnt(5)
	v_pk_mul_f32 v[76:77], v[76:77], v[204:205]
	s_waitcnt lgkmcnt(4)
	v_pk_mul_f32 v[78:79], v[78:79], v[206:207]
	s_nop 1
	v_mfma_f32_16x16x32_bf16 v[76:79], v[248:251], v[200:203], v[76:79]
	s_sub_u32 s98, s24, 6
	s_cmp_le_u32 s98, 57
	s_cbranch_scc0 .Lgla_wcons_4
	s_waitcnt vmcnt(22)
	s_branch .Lgla_wdone_4

; DI bf16x8 tr2(const bf16_t* p0, const bf16_t* p1) { s16x4 a = trread(p0), b = trread(p1); return __builtin_shufflevector(a, b, 0, 1, 2, 3, 4, 5, 6, 7); }
; DI f32x4 mfma16(bf16x8 a, bf16x8 b, f32x4 c) { return __builtin_amdgcn_mfma_f32_16x16x32_bf16(a, b, c, 0, 0, 0); }
; DI void gla_scan_item(const P& p, int seq, unsigned char* smem) {
;     ...
;     auto loadr = [&](GlaRegs& R, int c) {
;         if (c >= 72) return;
;         { const int pos = tid >> 4, ch = tid & 15; R.rv = *(const u32x4*)(S + (size_t)prow(b, dir, 32 * c + pos) * NP + C_GLA_V + 128 * h + 8 * ch); }
;         { const int t2 = tid & 255, pos = t2 >> 3, ch = t2 & 7; const bf16_t* src = (tid < 256 ? QT : KO) + ((size_t)seq * PT + 32 * c + pos) * 64 + 8 * ch; R.rq = __builtin_nontemporal_load((const u32x4*)src); }
;         if (tid < 128) { const int i = tid >> 2, ch = tid & 3; R.ra = __builtin_nontemporal_load((const u32x4*)(AT + (((size_t)seq * 72 + c) * 32 + i) * 32 + 8 * ch)); }
;         if (tid >= 128 && tid < 192) R.rd = DC[((size_t)seq * 72 + c) * 64 + (tid - 128)];
;     };
;     auto storel = [&](const GlaRegs& R, int buf) {
;         unsigned char* base = smem + buf * BUFB;
;         bf16_t* sat = (bf16_t*)base; bf16_t* sqt = (bf16_t*)(base + 2560); bf16_t* sko = (bf16_t*)(base + 2560 + 4608); bf16_t* sv = (bf16_t*)(base + 2560 + 9216); float* sdc = (float*)(base + 2560 + 9216 + 8704);
;         { const int pos = tid >> 4, ch = tid & 15; *(u32x4*)(sv + pos * 136 + 8 * ch) = R.rv; }
;         { const int t2 = tid & 255, pos = t2 >> 3, ch = t2 & 7; *(u32x4*)((tid < 256 ? sqt : sko) + pos * 72 + 8 * ch) = R.rq; }
;         if (tid < 128) { const int i = tid >> 2, ch = tid & 3; *(u32x4*)(sat + i * 40 + 8 * ch) = R.ra; }
;         if (tid >= 128 && tid < 192) sdc[tid - 128] = R.rd;
;     };
;     ...
;         for (int dt = 0; dt < 4; ++dt) {
;             const bf16x8 ak = tr2(sko + (8 * g + q4) * 72 + 16 * dt + 4 * p4, sko + (8 * g + 4 + q4) * 72 + 16 * dt + 4 * p4);
; #pragma unroll
;             for (int r = 0; r < 4; ++r) st[dt][r] *= sdc[16 * dt + 4 * g + r];
;             st[dt] = mfma16(ak, vb, st[dt]);
;         }
;     };
.Lgla_wdone_4:
	ds_write_b128 v121, v[36:39] offset:32512
	ds_write_b128 v122, v[44:47] offset:20736
	s_waitcnt lgkmcnt(3)
	v_pk_mul_f32 v[80:81], v[80:81], v[212:213]
	s_waitcnt lgkmcnt(2)
	v_pk_mul_f32 v[82:83], v[82:83], v[214:215]
	s_nop 1
	v_mfma_f32_16x16x32_bf16 v[80:83], v[208:211], v[200:203], v[80:83]
	s_and_saveexec_b64 s[36:37], s[38:39]
	ds_write_b128 v148, v[40:43] offset:20736
	s_or_b64 exec, exec, s[36:37]
	s_and_saveexec_b64 s[36:37], s[40:41]
	ds_write_b32 v149, v118 offset:40704
	s_or_b64 exec, exec, s[36:37]
	s_cmp_gt_u32 s24, 62
	s_waitcnt lgkmcnt(0)
	s_barrier
	ds_read_b64_tr_b16 v[200:201], v123 offset:32512
	ds_read_b64_tr_b16 v[202:203], v124 offset:32512
	ds_read_b128 v[204:207], v125 offset:20736
	ds_read2_b64 v[208:211], v159 offset0:96 offset1:100
	ds_read2_b64 v[212:215], v159 offset0:104 offset1:108
	ds_read2_b64 v[216:219], v162 offset0:96 offset1:100
	ds_read_b128 v[224:227], v127 offset:20736
	ds_read2_b64 v[228:231], v162 offset0:104 offset1:108
	ds_read2_b32 v[232:233], v163 offset1:1
	ds_read2_b32 v[234:235], v183 offset1:1
	ds_read_b64_tr_b16 v[238:239], v147 offset:27904
	ds_read_b64_tr_b16 v[242:243], v147 offset:27936
	s_cbranch_scc1 .LBB0_620
	v_add_u32_e32 v36, 0xe0, v150
	s_movk_i32 s2, 0x100
	v_cmp_gt_i32_e32 vcc, s2, v36
	v_subrev_u32_e32 v37, 32, v150
	v_mov_b32_e32 v39, s22
	v_cndmask_b32_e32 v38, v174, v175, vcc
	v_add3_u32 v38, v132, v38, s27
	v_cndmask_b32_e32 v36, v37, v36, vcc
	v_mov_b32_e32 v37, s21
	v_add_u32_e32 v38, 0xfffff681, v38
	v_cndmask_b32_e32 v37, v37, v39, vcc
	v_cndmask_b32_e64 v36, v38, v36, s[0:1]
	v_add_u32_e32 v36, v36, v37
	s_movk_i32 s2, 0x3800
	v_add_co_u32_e32 v44, vcc, 0x9000, v112
	v_mad_i64_i32 v[36:37], s[2:3], v36, s2, v[104:105]
	s_nop 0
	v_addc_co_u32_e32 v45, vcc, 0, v113, vcc
	global_load_dwordx4 v[36:39], v[36:37], off offset:1024
	s_nop 0
	global_load_dwordx4 v[44:47], v[44:45], off nt
	s_and_saveexec_b64 s[36:37], s[38:39]
	s_cbranch_execz .LBB0_617
	v_lshl_add_u64 v[40:41], v[106:107], 0, s[44:45]
	v_add_co_u32_e32 v40, vcc, 0x12840000, v40
	s_nop 1
	v_addc_co_u32_e32 v41, vcc, 0, v41, vcc
	global_load_dwordx4 v[40:43], v[40:41], off offset:2048 nt

; DI bf16x8 tr2(const bf16_t* p0, const bf16_t* p1) { s16x4 a = trread(p0), b = trread(p1); return __builtin_shufflevector(a, b, 0, 1, 2, 3, 4, 5, 6, 7); }
; DI f32x4 mfma16(bf16x8 a, bf16x8 b, f32x4 c) { return __builtin_amdgcn_mfma_f32_16x16x32_bf16(a, b, c, 0, 0, 0); }
; DI void gla_scan_item(const P& p, int seq, unsigned char* smem) {
;     ...
;     auto compute = [&](int c) {
;         const unsigned char* base = smem + (c & 1) * BUFB;
;         const bf16_t* sat = (const bf16_t*)base; const bf16_t* sqt = (const bf16_t*)(base + 2560); const bf16_t* sko = (const bf16_t*)(base + 2560 + 4608); const bf16_t* sv = (const bf16_t*)(base + 2560 + 9216); const float* sdc = (const float*)(base + 2560 + 9216 + 8704);
;         const int dv0 = 16 * w;
;         const bf16x8 vb = tr2(sv + (8 * g + q4) * 136 + dv0 + 4 * p4, sv + (8 * g + 4 + q4) * 136 + dv0 + 4 * p4);
;         bf16x8 bs[2];
;         bs[0] = packacc(st[0], st[1]); bs[1] = packacc(st[2], st[3]);
; #pragma unroll
;         for (int mt = 0; mt < 2; ++mt) {
;             f32x4 acc = (f32x4){0.f, 0.f, 0.f, 0.f};
;             acc = mfma16(vb, ld8(sat + (16 * mt + l15) * 40 + 8 * g), acc);
; #pragma unroll
;             for (int ks = 0; ks < 2; ++ks) {
;                 const bf16_t* r0 = sqt + (16 * mt + l15) * 72 + 32 * ks + 4 * g;
;                 acc = mfma16(bs[ks], ld4x2(r0, r0 + 16), acc);
;             }
;             bf16_t* ob = OG + (size_t)prow(b, dir, 32 * c) * 512 + 128 * h;
;             u32x2 ov; ov.x = pk2(acc[0], acc[1]); ov.y = pk2(acc[2], acc[3]);
;             *(u32x2*)(ob + sgn * ((16 * mt + l15) * 512) + dv0 + 4 * g) = ov;
;         }
; #pragma unroll
;         for (int dt = 0; dt < 4; ++dt) {
;             const bf16x8 ak = tr2(sko + (8 * g + q4) * 72 + 16 * dt + 4 * p4, sko + (8 * g + 4 + q4) * 72 + 16 * dt + 4 * p4);
; #pragma unroll
;             for (int r = 0; r < 4; ++r) st[dt][r] *= sdc[16 * dt + 4 * g + r];
;             st[dt] = mfma16(ak, vb, st[dt]);
;         }
;     };
.LBB0_620:
	v_cvt_pk_bf16_f32 v98, v72, v73
	v_cvt_pk_bf16_f32 v97, v90, v91
	v_cvt_pk_bf16_f32 v96, v88, v89
	v_cvt_pk_bf16_f32 v99, v74, v75
	s_waitcnt lgkmcnt(9)
	v_mfma_f32_16x16x32_bf16 v[92:95], v[200:203], v[204:207], 0
	ds_read_b64_tr_b16 v[236:237], v146 offset:27904
	ds_read_b64_tr_b16 v[240:241], v146 offset:27936
	ds_read2_b32 v[244:245], v185 offset1:1
	s_add_i32 s4, s26, 32
	s_add_i32 s5, s26, 0xffffff20
	s_add_i32 s6, s27, 64
	s_add_i32 s7, s27, 0xfffff840
	s_and_b64 s[2:3], s[0:1], exec
	s_cselect_b32 s2, s4, s7
	s_waitcnt lgkmcnt(11)
	v_mfma_f32_16x16x32_bf16 v[92:95], v[96:99], v[208:211], v[92:95]
	ds_read2_b32 v[246:247], v184 offset1:1
	v_cvt_pk_bf16_f32 v190, v80, v81
	v_cvt_pk_bf16_f32 v189, v78, v79
	v_cvt_pk_bf16_f32 v188, v76, v77
	v_cvt_pk_bf16_f32 v191, v82, v83
	s_add_i32 s4, s2, s22
	s_and_b64 s[2:3], s[0:1], exec
	s_cselect_b32 s2, s5, s6
	s_add_i32 s2, s2, s21
	s_cmp_lt_u32 s24, 5
	s_waitcnt lgkmcnt(11)
	v_mfma_f32_16x16x32_bf16 v[92:95], v[188:191], v[212:215], v[92:95]
	ds_read_b64_tr_b16 v[248:249], v146 offset:27968
	s_cselect_b32 s2, s4, s2
	s_ashr_i32 s3, s2, 31
	s_lshl_b64 s[36:37], s[2:3], 10
	s_nop 3
	v_cvt_pk_bf16_f32 v92, v92, v93
	v_cvt_pk_bf16_f32 v93, v94, v95
	v_lshl_add_u64 v[94:95], v[100:101], 0, s[36:37]
	global_store_dwordx2 v[94:95], v[92:93], off
	s_waitcnt lgkmcnt(10)
	v_mfma_f32_16x16x32_bf16 v[92:95], v[200:203], v[224:227], 0
	ds_read_b64_tr_b16 v[250:251], v147 offset:27968
	ds_read2_b32 v[204:205], v164 offset1:1
	v_mfma_f32_16x16x32_bf16 v[92:95], v[96:99], v[216:219], v[92:95]
	s_waitcnt lgkmcnt(11)
	v_mfma_f32_16x16x32_bf16 v[92:95], v[188:191], v[228:231], v[92:95]
	ds_read2_b32 v[206:207], v165 offset1:1
	s_nop 7
	v_cvt_pk_bf16_f32 v92, v92, v93
	v_cvt_pk_bf16_f32 v93, v94, v95
	v_lshl_add_u64 v[94:95], v[102:103], 0, s[36:37]
	global_store_dwordx2 v[94:95], v[92:93], off
	s_waitcnt lgkmcnt(11)
	v_pk_mul_f32 v[88:89], v[88:89], v[232:233]
	ds_read_b64_tr_b16 v[208:209], v146 offset:28000
	s_waitcnt lgkmcnt(11)
	v_pk_mul_f32 v[90:91], v[90:91], v[234:235]
	ds_read_b64_tr_b16 v[210:211], v147 offset:28000
	s_waitcnt lgkmcnt(9)
	v_mfma_f32_16x16x32_bf16 v[88:91], v[236:239], v[200:203], v[88:91]
	ds_read2_b32 v[212:213], v187 offset1:1
	ds_read2_b32 v[214:215], v186 offset1:1
	s_waitcnt lgkmcnt(9)
	v_pk_mul_f32 v[72:73], v[72:73], v[244:245]
	s_waitcnt lgkmcnt(8)
	v_pk_mul_f32 v[74:75], v[74:75], v[246:247]
	s_nop 1
	v_mfma_f32_16x16x32_bf16 v[72:75], v[240:243], v[200:203], v[72:75]
	s_waitcnt lgkmcnt(5)
	v_pk_mul_f32 v[76:77], v[76:77], v[204:205]
	s_waitcnt lgkmcnt(4)
	v_pk_mul_f32 v[78:79], v[78:79], v[206:207]
	s_nop 1
	v_mfma_f32_16x16x32_bf16 v[76:79], v[248:251], v[200:203], v[76:79]
	s_sub_u32 s98, s24, 6
	s_cmp_le_u32 s98, 56
	s_cbranch_scc0 .Lgla_wcons_5
	s_waitcnt vmcnt(22)
	s_branch .Lgla_wdone_5

; DI bf16x8 tr2(const bf16_t* p0, const bf16_t* p1) { s16x4 a = trread(p0), b = trread(p1); return __builtin_shufflevector(a, b, 0, 1, 2, 3, 4, 5, 6, 7); }
; DI f32x4 mfma16(bf16x8 a, bf16x8 b, f32x4 c) { return __builtin_amdgcn_mfma_f32_16x16x32_bf16(a, b, c, 0, 0, 0); }
; DI void gla_scan_item(const P& p, int seq, unsigned char* smem) {
;     ...
;     auto loadr = [&](GlaRegs& R, int c) {
;         if (c >= 72) return;
;         { const int pos = tid >> 4, ch = tid & 15; R.rv = *(const u32x4*)(S + (size_t)prow(b, dir, 32 * c + pos) * NP + C_GLA_V + 128 * h + 8 * ch); }
;         { const int t2 = tid & 255, pos = t2 >> 3, ch = t2 & 7; const bf16_t* src = (tid < 256 ? QT : KO) + ((size_t)seq * PT + 32 * c + pos) * 64 + 8 * ch; R.rq = __builtin_nontemporal_load((const u32x4*)src); }
;         if (tid < 128) { const int i = tid >> 2, ch = tid & 3; R.ra = __builtin_nontemporal_load((const u32x4*)(AT + (((size_t)seq * 72 + c) * 32 + i) * 32 + 8 * ch)); }
;         if (tid >= 128 && tid < 192) R.rd = DC[((size_t)seq * 72 + c) * 64 + (tid - 128)];
;     };
;     auto storel = [&](const GlaRegs& R, int buf) {
;         unsigned char* base = smem + buf * BUFB;
;         bf16_t* sat = (bf16_t*)base; bf16_t* sqt = (bf16_t*)(base + 2560); bf16_t* sko = (bf16_t*)(base + 2560 + 4608); bf16_t* sv = (bf16_t*)(base + 2560 + 9216); float* sdc = (float*)(base + 2560 + 9216 + 8704);
;         { const int pos = tid >> 4, ch = tid & 15; *(u32x4*)(sv + pos * 136 + 8 * ch) = R.rv; }
;         { const int t2 = tid & 255, pos = t2 >> 3, ch = t2 & 7; *(u32x4*)((tid < 256 ? sqt : sko) + pos * 72 + 8 * ch) = R.rq; }
;         if (tid < 128) { const int i = tid >> 2, ch = tid & 3; *(u32x4*)(sat + i * 40 + 8 * ch) = R.ra; }
;         if (tid >= 128 && tid < 192) sdc[tid - 128] = R.rd;
;     };
;     ...
;         for (int dt = 0; dt < 4; ++dt) {
;             const bf16x8 ak = tr2(sko + (8 * g + q4) * 72 + 16 * dt + 4 * p4, sko + (8 * g + 4 + q4) * 72 + 16 * dt + 4 * p4);
; #pragma unroll
;             for (int r = 0; r < 4; ++r) st[dt][r] *= sdc[16 * dt + 4 * g + r];
;             st[dt] = mfma16(ak, vb, st[dt]);
;         }
;     };
.Lgla_wdone_5:
	ds_write_b128 v121, v[48:51] offset:11776
	ds_write_b128 v122, v[56:59]
	s_waitcnt lgkmcnt(3)
	v_pk_mul_f32 v[80:81], v[80:81], v[212:213]
	s_waitcnt lgkmcnt(2)
	v_pk_mul_f32 v[82:83], v[82:83], v[214:215]
	s_nop 1
	v_mfma_f32_16x16x32_bf16 v[84:87], v[208:211], v[200:203], v[80:83]
	s_and_saveexec_b64 s[36:37], s[38:39]
	ds_write_b128 v148, v[52:55]
	s_or_b64 exec, exec, s[36:37]
	s_and_saveexec_b64 s[36:37], s[40:41]
	ds_write_b32 v149, v119 offset:19968
	s_or_b64 exec, exec, s[36:37]
	s_cmp_gt_u32 s24, 61
	s_waitcnt lgkmcnt(0)
	s_barrier
	ds_read_b64_tr_b16 v[200:201], v123 offset:11776
	ds_read_b64_tr_b16 v[202:203], v124 offset:11776
	ds_read_b128 v[204:207], v125
	ds_read2_b64 v[208:211], v152 offset0:64 offset1:68
	ds_read2_b64 v[212:215], v152 offset0:72 offset1:76
	ds_read2_b64 v[216:219], v151 offset0:64 offset1:68
	ds_read_b128 v[224:227], v127
	ds_read2_b64 v[228:231], v151 offset0:72 offset1:76
	ds_read2_b32 v[232:233], v153 offset1:1
	ds_read2_b32 v[234:235], v156 offset1:1
	ds_read_b64_tr_b16 v[238:239], v144 offset:7168
	ds_read_b64_tr_b16 v[242:243], v144 offset:7200
	s_cbranch_scc1 .LBB0_630
	v_add_u32_e32 v48, 0x100, v150
	s_movk_i32 s2, 0x100
	v_cmp_gt_i32_e32 vcc, s2, v48
	v_mov_b32_e32 v50, s21
	v_mov_b32_e32 v51, s22
	v_cndmask_b32_e32 v49, v174, v175, vcc
	v_add3_u32 v49, v132, v49, s27
	v_cndmask_b32_e32 v48, v150, v48, vcc
	v_add_u32_e32 v49, 0xfffff661, v49
	v_cndmask_b32_e32 v50, v50, v51, vcc
	v_cndmask_b32_e64 v48, v49, v48, s[0:1]
	v_add_u32_e32 v48, v48, v50
	s_movk_i32 s2, 0x3800
	v_add_co_u32_e32 v56, vcc, 0xa000, v112
	v_mad_i64_i32 v[48:49], s[2:3], v48, s2, v[104:105]
	s_nop 0
	v_addc_co_u32_e32 v57, vcc, 0, v113, vcc
	global_load_dwordx4 v[48:51], v[48:49], off offset:1024
	s_nop 0
	global_load_dwordx4 v[56:59], v[56:57], off nt
	s_and_saveexec_b64 s[36:37], s[38:39]
	s_cbranch_execz .LBB0_627
	v_lshl_add_u64 v[52:53], v[106:107], 0, s[44:45]
	v_add_co_u32_e32 v52, vcc, 0x12841000, v52
	s_nop 1
	v_addc_co_u32_e32 v53, vcc, 0, v53, vcc
	global_load_dwordx4 v[52:55], v[52:53], off nt

; DI bf16x8 tr2(const bf16_t* p0, const bf16_t* p1) { s16x4 a = trread(p0), b = trread(p1); return __builtin_shufflevector(a, b, 0, 1, 2, 3, 4, 5, 6, 7); }
; DI f32x4 mfma16(bf16x8 a, bf16x8 b, f32x4 c) { return __builtin_amdgcn_mfma_f32_16x16x32_bf16(a, b, c, 0, 0, 0); }
; DI void gla_scan_item(const P& p, int seq, unsigned char* smem) {
;     ...
;     auto compute = [&](int c) {
;         const unsigned char* base = smem + (c & 1) * BUFB;
;         const bf16_t* sat = (const bf16_t*)base; const bf16_t* sqt = (const bf16_t*)(base + 2560); const bf16_t* sko = (const bf16_t*)(base + 2560 + 4608); const bf16_t* sv = (const bf16_t*)(base + 2560 + 9216); const float* sdc = (const float*)(base + 2560 + 9216 + 8704);
;         const int dv0 = 16 * w;
;         const bf16x8 vb = tr2(sv + (8 * g + q4) * 136 + dv0 + 4 * p4, sv + (8 * g + 4 + q4) * 136 + dv0 + 4 * p4);
;         bf16x8 bs[2];
;         bs[0] = packacc(st[0], st[1]); bs[1] = packacc(st[2], st[3]);
; #pragma unroll
;         for (int mt = 0; mt < 2; ++mt) {
;             f32x4 acc = (f32x4){0.f, 0.f, 0.f, 0.f};
;             acc = mfma16(vb, ld8(sat + (16 * mt + l15) * 40 + 8 * g), acc);
; #pragma unroll
;             for (int ks = 0; ks < 2; ++ks) {
;                 const bf16_t* r0 = sqt + (16 * mt + l15) * 72 + 32 * ks + 4 * g;
;                 acc = mfma16(bs[ks], ld4x2(r0, r0 + 16), acc);
;             }
;             bf16_t* ob = OG + (size_t)prow(b, dir, 32 * c) * 512 + 128 * h;
;             u32x2 ov; ov.x = pk2(acc[0], acc[1]); ov.y = pk2(acc[2], acc[3]);
;             *(u32x2*)(ob + sgn * ((16 * mt + l15) * 512) + dv0 + 4 * g) = ov;
;         }
; #pragma unroll
;         for (int dt = 0; dt < 4; ++dt) {
;             const bf16x8 ak = tr2(sko + (8 * g + q4) * 72 + 16 * dt + 4 * p4, sko + (8 * g + 4 + q4) * 72 + 16 * dt + 4 * p4);
; #pragma unroll
;             for (int r = 0; r < 4; ++r) st[dt][r] *= sdc[16 * dt + 4 * g + r];
;             st[dt] = mfma16(ak, vb, st[dt]);
;         }
;     };
.LBB0_630:
	v_cvt_pk_bf16_f32 v94, v72, v73
	v_cvt_pk_bf16_f32 v93, v90, v91
	v_cvt_pk_bf16_f32 v92, v88, v89
	v_cvt_pk_bf16_f32 v95, v74, v75
	s_waitcnt lgkmcnt(9)
	v_mfma_f32_16x16x32_bf16 v[80:83], v[200:203], v[204:207], 0
	ds_read_b64_tr_b16 v[236:237], v143 offset:7168
	ds_read_b64_tr_b16 v[240:241], v143 offset:7200
	ds_read2_b32 v[244:245], v158 offset1:1
	s_add_i32 s4, s26, 64
	s_add_i32 s5, s26, 0xffffff40
	s_add_i32 s6, s27, 32
	s_add_i32 s7, s27, 0xfffff820
	s_and_b64 s[2:3], s[0:1], exec
	s_cselect_b32 s2, s4, s7
	s_waitcnt lgkmcnt(11)
	v_mfma_f32_16x16x32_bf16 v[80:83], v[92:95], v[208:211], v[80:83]
	ds_read2_b32 v[246:247], v157 offset1:1
	v_cvt_pk_bf16_f32 v190, v84, v85
	v_cvt_pk_bf16_f32 v189, v78, v79
	v_cvt_pk_bf16_f32 v188, v76, v77
	v_cvt_pk_bf16_f32 v191, v86, v87
	s_add_i32 s4, s2, s22
	s_and_b64 s[2:3], s[0:1], exec
	s_cselect_b32 s2, s5, s6
	s_add_i32 s2, s2, s21
	s_cmp_lt_u32 s24, 4
	s_waitcnt lgkmcnt(11)
	v_mfma_f32_16x16x32_bf16 v[80:83], v[188:191], v[212:215], v[80:83]
	ds_read_b64_tr_b16 v[248:249], v143 offset:7232
	s_cselect_b32 s2, s4, s2
	s_ashr_i32 s3, s2, 31
	s_lshl_b64 s[36:37], s[2:3], 10
	s_nop 3
	v_cvt_pk_bf16_f32 v80, v80, v81
	v_cvt_pk_bf16_f32 v81, v82, v83
	v_lshl_add_u64 v[82:83], v[100:101], 0, s[36:37]
	global_store_dwordx2 v[82:83], v[80:81], off
	s_waitcnt lgkmcnt(10)
	v_mfma_f32_16x16x32_bf16 v[80:83], v[200:203], v[224:227], 0
	ds_read_b64_tr_b16 v[250:251], v144 offset:7232
	ds_read2_b32 v[204:205], v154 offset1:1
	v_mfma_f32_16x16x32_bf16 v[80:83], v[92:95], v[216:219], v[80:83]
	s_waitcnt lgkmcnt(11)
	v_mfma_f32_16x16x32_bf16 v[80:83], v[188:191], v[228:231], v[80:83]
	ds_read2_b32 v[206:207], v155 offset1:1
	s_nop 7
	v_cvt_pk_bf16_f32 v80, v80, v81
	v_cvt_pk_bf16_f32 v81, v82, v83
	v_lshl_add_u64 v[82:83], v[102:103], 0, s[36:37]
	global_store_dwordx2 v[82:83], v[80:81], off
	s_waitcnt lgkmcnt(11)
	v_pk_mul_f32 v[80:81], v[88:89], v[232:233]
	ds_read_b64_tr_b16 v[208:209], v143 offset:7264
	s_waitcnt lgkmcnt(11)
	v_pk_mul_f32 v[82:83], v[90:91], v[234:235]
	ds_read_b64_tr_b16 v[210:211], v144 offset:7264
	s_waitcnt lgkmcnt(9)
	v_mfma_f32_16x16x32_bf16 v[92:95], v[236:239], v[200:203], v[80:83]
	ds_read2_b32 v[212:213], v161 offset1:1
	ds_read2_b32 v[214:215], v160 offset1:1
	s_nop 2
	s_waitcnt lgkmcnt(9)
	v_pk_mul_f32 v[72:73], v[72:73], v[244:245]
	s_waitcnt lgkmcnt(8)
	v_pk_mul_f32 v[74:75], v[74:75], v[246:247]
	s_nop 1
	v_mfma_f32_16x16x32_bf16 v[72:75], v[240:243], v[200:203], v[72:75]
	s_waitcnt lgkmcnt(5)
	v_pk_mul_f32 v[76:77], v[76:77], v[204:205]
	s_waitcnt lgkmcnt(4)
	v_pk_mul_f32 v[78:79], v[78:79], v[206:207]
	s_nop 1
	v_mfma_f32_16x16x32_bf16 v[80:83], v[248:251], v[200:203], v[76:79]
	s_nop 2
	s_sub_u32 s98, s24, 6
	s_cmp_le_u32 s98, 55
	s_cbranch_scc0 .Lgla_wcons_6
	s_waitcnt vmcnt(22)
	s_branch .Lgla_wdone_6

; DI void gla_scan_item(const P& p, int seq, unsigned char* smem) {
;     ...
;     auto loadr = [&](GlaRegs& R, int c) {
;         if (c >= 72) return;
;         { const int pos = tid >> 4, ch = tid & 15; R.rv = *(const u32x4*)(S + (size_t)prow(b, dir, 32 * c + pos) * NP + C_GLA_V + 128 * h + 8 * ch); }
;         { const int t2 = tid & 255, pos = t2 >> 3, ch = t2 & 7; const bf16_t* src = (tid < 256 ? QT : KO) + ((size_t)seq * PT + 32 * c + pos) * 64 + 8 * ch; R.rq = __builtin_nontemporal_load((const u32x4*)src); }
;         if (tid < 128) { const int i = tid >> 2, ch = tid & 3; R.ra = __builtin_nontemporal_load((const u32x4*)(AT + (((size_t)seq * 72 + c) * 32 + i) * 32 + 8 * ch)); }
;         if (tid >= 128 && tid < 192) R.rd = DC[((size_t)seq * 72 + c) * 64 + (tid - 128)];
;     };
;     auto storel = [&](const GlaRegs& R, int buf) {
;         unsigned char* base = smem + buf * BUFB;
;         bf16_t* sat = (bf16_t*)base; bf16_t* sqt = (bf16_t*)(base + 2560); bf16_t* sko = (bf16_t*)(base + 2560 + 4608); bf16_t* sv = (bf16_t*)(base + 2560 + 9216); float* sdc = (float*)(base + 2560 + 9216 + 8704);
;         { const int pos = tid >> 4, ch = tid & 15; *(u32x4*)(sv + pos * 136 + 8 * ch) = R.rv; }
;         { const int t2 = tid & 255, pos = t2 >> 3, ch = t2 & 7; *(u32x4*)((tid < 256 ? sqt : sko) + pos * 72 + 8 * ch) = R.rq; }
;         if (tid < 128) { const int i = tid >> 2, ch = tid & 3; *(u32x4*)(sat + i * 40 + 8 * ch) = R.ra; }
;         if (tid >= 128 && tid < 192) sdc[tid - 128] = R.rd;
;     };
;     ...
; #pragma unroll 1
;     for (int c = 0; c < 72; c += 6) {
;         storel(R0, 0); __syncthreads(); loadr(R0, c + 6); compute(c);
.Lgla_wdone_6:
	ds_write_b128 v121, v[60:63] offset:32512
	ds_write_b128 v122, v[68:71] offset:20736
	s_waitcnt lgkmcnt(3)
	v_pk_mul_f32 v[84:85], v[84:85], v[212:213]
	s_waitcnt lgkmcnt(2)
	v_pk_mul_f32 v[86:87], v[86:87], v[214:215]
	s_nop 1
	v_mfma_f32_16x16x32_bf16 v[88:91], v[208:211], v[200:203], v[84:87]
	s_and_saveexec_b64 s[36:37], s[38:39]
	ds_write_b128 v148, v[64:67] offset:20736
	s_or_b64 exec, exec, s[36:37]
	s_and_saveexec_b64 s[36:37], s[40:41]
	ds_write_b32 v149, v120 offset:40704
	s_or_b64 exec, exec, s[36:37]
	s_cmp_gt_u32 s24, 60
	s_waitcnt lgkmcnt(0)
	s_barrier
	s_cbranch_scc1 .LBB0_579
	v_add_u32_e32 v60, 0x120, v150
	s_movk_i32 s2, 0x100
	v_cmp_gt_i32_e32 vcc, s2, v60
	v_add_u32_e32 v61, 32, v150
	v_mov_b32_e32 v63, s22
	v_cndmask_b32_e32 v62, v174, v175, vcc
	v_add3_u32 v62, v132, v62, s27
	v_cndmask_b32_e32 v60, v61, v60, vcc
	v_mov_b32_e32 v61, s21
	v_add_u32_e32 v62, 0xfffff641, v62
	v_cndmask_b32_e32 v61, v61, v63, vcc
	v_cndmask_b32_e64 v60, v62, v60, s[0:1]
	v_add_u32_e32 v60, v60, v61
	s_movk_i32 s2, 0x3800
	v_add_co_u32_e32 v68, vcc, 0xb000, v112
	v_mad_i64_i32 v[60:61], s[2:3], v60, s2, v[104:105]
	s_nop 0
	v_addc_co_u32_e32 v69, vcc, 0, v113, vcc
	global_load_dwordx4 v[60:63], v[60:61], off offset:1024
	s_nop 0
	global_load_dwordx4 v[68:71], v[68:69], off nt
	s_and_saveexec_b64 s[36:37], s[38:39]
	s_cbranch_execz .LBB0_637
	v_lshl_add_u64 v[64:65], v[106:107], 0, s[44:45]
	v_add_co_u32_e32 v64, vcc, 0x12841000, v64
	s_nop 1
	v_addc_co_u32_e32 v65, vcc, 0, v65, vcc
	global_load_dwordx4 v[64:67], v[64:65], off offset:2048 nt
